# attention DMA sequences: m0 written directly by s_add_i32 and V2 reuses V1's LDS offset (7 fewer SALU per step), on top of prio+VALU diet
# baseline (speedup 1.0000x reference)
.LBB0_304:
	s_mov_b32 s37, s28
	s_mov_b32 s14, s27
	v_lshl_add_u32 v65, s15, 1, v239
	ds_read_b64_tr_b16 v[72:73], v65 offset:24576
	ds_read_b64_tr_b16 v[74:75], v65 offset:25088
	v_add_f32_e32 v68, v96, v97
	v_add_f32_e32 v68, v98, v68
	v_add_f32_e32 v68, v99, v68
	v_add_f32_e32 v68, v100, v68
	v_add_f32_e32 v68, v101, v68
	v_cvt_pk_bf16_f32 v172, v96, v97
	v_cvt_pk_bf16_f32 v173, v98, v99
	s_waitcnt lgkmcnt(9)
	v_mfma_f32_32x32x16_bf16 v[128:143], v[204:207], v[168:171], 0
	ds_read_b64_tr_b16 v[76:77], v65 offset:28672
	ds_read_b64_tr_b16 v[78:79], v65 offset:29184
	v_add_f32_e32 v68, v102, v68
	v_add_f32_e32 v68, v103, v68
	v_add_f32_e32 v68, v104, v68
	v_add_f32_e32 v68, v105, v68
	v_cvt_pk_bf16_f32 v174, v100, v101
	v_cvt_pk_bf16_f32 v175, v102, v103
	s_waitcnt lgkmcnt(10)
	v_mfma_f32_32x32x16_bf16 v[112:127], v[200:203], v[168:171], 0
	ds_read_b64_tr_b16 v[96:97], v65 offset:32768
	ds_read_b64_tr_b16 v[98:99], v65 offset:33280
	v_add_f32_e32 v68, v106, v68
	v_add_f32_e32 v68, v107, v68
	v_add_f32_e32 v68, v108, v68
	v_add_f32_e32 v68, v109, v68
	v_cvt_pk_bf16_f32 v164, v104, v105
	v_cvt_pk_bf16_f32 v165, v106, v107
	s_waitcnt lgkmcnt(11)
	v_mfma_f32_32x32x16_bf16 v[128:143], v[196:199], v[160:163], v[128:143]
	ds_read_b64_tr_b16 v[100:101], v65 offset:36864
	ds_read_b64_tr_b16 v[102:103], v65 offset:37376
	v_add_f32_e32 v68, v110, v68
	v_add_f32_e32 v68, v111, v68
	v_add_f32_e32 v68, v80, v68
	v_add_f32_e32 v68, v81, v68
	v_cvt_pk_bf16_f32 v166, v108, v109
	v_cvt_pk_bf16_f32 v167, v110, v111
	s_waitcnt lgkmcnt(12)
	v_mfma_f32_32x32x16_bf16 v[112:127], v[192:195], v[160:163], v[112:127]
	ds_read_b64_tr_b16 v[104:105], v65 offset:25600
	ds_read_b64_tr_b16 v[106:107], v65 offset:26112
	v_add_f32_e32 v68, v82, v68
	v_add_f32_e32 v68, v83, v68
	v_add_f32_e32 v68, v84, v68
	v_add_f32_e32 v68, v85, v68
	v_cvt_pk_bf16_f32 v156, v80, v81
	v_cvt_pk_bf16_f32 v157, v82, v83
	s_waitcnt lgkmcnt(13)
	v_mfma_f32_32x32x16_bf16 v[128:143], v[188:191], v[152:155], v[128:143]
	ds_read_b64_tr_b16 v[80:81], v65 offset:29696
	ds_read_b64_tr_b16 v[82:83], v65 offset:30208
	v_add_f32_e32 v68, v86, v68
	v_add_f32_e32 v68, v87, v68
	v_add_f32_e32 v68, v88, v68
	v_add_f32_e32 v68, v89, v68
	v_cvt_pk_bf16_f32 v158, v84, v85
	v_cvt_pk_bf16_f32 v159, v86, v87
	s_waitcnt lgkmcnt(14)
	v_mfma_f32_32x32x16_bf16 v[112:127], v[184:187], v[152:155], v[112:127]
	ds_read_b64_tr_b16 v[84:85], v65 offset:33792
	ds_read_b64_tr_b16 v[86:87], v65 offset:34304
	v_add_f32_e32 v68, v90, v68
	v_add_f32_e32 v68, v91, v68
	v_add_f32_e32 v68, v92, v68
	v_add_f32_e32 v68, v93, v68
	v_cvt_pk_bf16_f32 v148, v88, v89
	v_cvt_pk_bf16_f32 v149, v90, v91
	s_waitcnt lgkmcnt(14)
	v_mfma_f32_32x32x16_bf16 v[128:143], v[180:183], v[144:147], v[128:143]
	ds_read_b64_tr_b16 v[88:89], v65 offset:37888
	ds_read_b64_tr_b16 v[90:91], v65 offset:38400
	v_add_f32_e32 v68, v94, v68
	v_add_f32_e32 v68, v95, v68
	v_cvt_pk_bf16_f32 v150, v92, v93
	v_cvt_pk_bf16_f32 v151, v94, v95
	v_mfma_f32_32x32x16_bf16 v[112:127], v[176:179], v[144:147], v[112:127]
	v_add_f32_e32 v64, v64, v68
	s_waitcnt lgkmcnt(14)
	v_mfma_f32_32x32x16_bf16 v[48:63], v[172:175], v[72:75], v[48:63]
	ds_read_b64_tr_b16 v[72:73], v65 offset:26624
	ds_read_b64_tr_b16 v[74:75], v65 offset:27136
	v_exp_f32_e32 v128, v128
	v_exp_f32_e32 v129, v129
	s_waitcnt lgkmcnt(14)
	v_mfma_f32_32x32x16_bf16 v[32:47], v[172:175], v[76:79], v[32:47]
	v_exp_f32_e32 v130, v130
	v_exp_f32_e32 v131, v131
	ds_read_b64_tr_b16 v[76:77], v65 offset:30720
	ds_read_b64_tr_b16 v[78:79], v65 offset:31232
	s_add_i32 m0, s27, s20
	s_nop 0
	global_load_lds_dwordx4 v250, s[98:99]
	s_add_u32 s98, s98, 0x60000
	s_addc_u32 s99, s99, 0
	s_waitcnt lgkmcnt(14)
	v_mfma_f32_32x32x16_bf16 v[16:31], v[172:175], v[96:99], v[16:31]
	v_exp_f32_e32 v132, v132
	v_exp_f32_e32 v133, v133
	ds_read_b64_tr_b16 v[92:93], v65 offset:34816
	ds_read_b64_tr_b16 v[94:95], v65 offset:35328
	s_waitcnt lgkmcnt(14)
	v_mfma_f32_32x32x16_bf16 v[0:15], v[172:175], v[100:103], v[0:15]
	v_exp_f32_e32 v134, v134
	v_exp_f32_e32 v135, v135
	ds_read_b64_tr_b16 v[96:97], v65 offset:38912
	ds_read_b64_tr_b16 v[98:99], v65 offset:39424
	s_waitcnt lgkmcnt(14)
	v_mfma_f32_32x32x16_bf16 v[48:63], v[164:167], v[104:107], v[48:63]
	v_exp_f32_e32 v136, v136
	v_exp_f32_e32 v137, v137
	ds_read_b64_tr_b16 v[100:101], v65 offset:27648
	ds_read_b64_tr_b16 v[102:103], v65 offset:28160
	s_lshl_b32 s15, s28, 1
	s_add_i32 s15, s15, s21
	s_mov_b32 m0, s15
	s_nop 0
	global_load_lds_dwordx4 v251, s[100:101]
	s_waitcnt lgkmcnt(14)
	v_mfma_f32_32x32x16_bf16 v[32:47], v[164:167], v[80:83], v[32:47]
	v_exp_f32_e32 v138, v138
	v_exp_f32_e32 v139, v139
	ds_read_b64_tr_b16 v[80:81], v65 offset:31744
	ds_read_b64_tr_b16 v[82:83], v65 offset:32256
	s_waitcnt lgkmcnt(14)
	v_mfma_f32_32x32x16_bf16 v[16:31], v[164:167], v[84:87], v[16:31]
	v_exp_f32_e32 v140, v140
	v_exp_f32_e32 v141, v141
	ds_read_b64_tr_b16 v[84:85], v65 offset:35840
	ds_read_b64_tr_b16 v[86:87], v65 offset:36352
	s_waitcnt lgkmcnt(14)
	v_mfma_f32_32x32x16_bf16 v[0:15], v[164:167], v[88:91], v[0:15]
	v_exp_f32_e32 v142, v142
	v_exp_f32_e32 v143, v143
	ds_read_b64_tr_b16 v[88:89], v65 offset:39936
	ds_read_b64_tr_b16 v[90:91], v65 offset:40448
	s_add_i32 m0, s15, 0x1f80
	s_nop 0
	global_load_lds_dwordx4 v251, s[100:101] offset:128
	s_add_u32 s100, s100, 0x60000
	s_addc_u32 s101, s101, 0
	s_waitcnt lgkmcnt(14)
	v_mfma_f32_32x32x16_bf16 v[48:63], v[156:159], v[72:75], v[48:63]
	v_exp_f32_e32 v112, v112
	v_exp_f32_e32 v113, v113
	s_waitcnt lgkmcnt(12)
	v_mfma_f32_32x32x16_bf16 v[32:47], v[156:159], v[76:79], v[32:47]
	v_exp_f32_e32 v114, v114
	v_exp_f32_e32 v115, v115
	v_add_u32_e32 v65, s37, v241
	ds_read_b128 v[72:75], v65
	ds_read_b128 v[76:79], v65 offset:512
	s_waitcnt lgkmcnt(12)
	v_mfma_f32_32x32x16_bf16 v[16:31], v[156:159], v[92:95], v[16:31]
	v_exp_f32_e32 v116, v116
	v_exp_f32_e32 v117, v117
	ds_read_b128 v[176:179], v65 offset:2048
	ds_read_b128 v[180:183], v65 offset:2560
	s_waitcnt lgkmcnt(12)
	v_mfma_f32_32x32x16_bf16 v[0:15], v[156:159], v[96:99], v[0:15]
	v_exp_f32_e32 v118, v118
	v_exp_f32_e32 v119, v119
	ds_read_b128 v[184:187], v65 offset:4096
	ds_read_b128 v[188:191], v65 offset:4608
	s_waitcnt lgkmcnt(12)
	v_mfma_f32_32x32x16_bf16 v[48:63], v[148:151], v[100:103], v[48:63]
	v_exp_f32_e32 v120, v120
	v_exp_f32_e32 v121, v121
	ds_read_b128 v[192:195], v65 offset:6144
	ds_read_b128 v[196:199], v65 offset:6656
	s_waitcnt lgkmcnt(12)
	v_mfma_f32_32x32x16_bf16 v[32:47], v[148:151], v[80:83], v[32:47]
	v_exp_f32_e32 v122, v122
	v_exp_f32_e32 v123, v123
	s_waitcnt lgkmcnt(10)
	v_mfma_f32_32x32x16_bf16 v[16:31], v[148:151], v[84:87], v[16:31]
	v_exp_f32_e32 v124, v124
	v_exp_f32_e32 v125, v125
	s_waitcnt lgkmcnt(8)
	v_mfma_f32_32x32x16_bf16 v[0:15], v[148:151], v[88:91], v[0:15]
	v_exp_f32_e32 v126, v126
	v_exp_f32_e32 v127, v127
	s_waitcnt vmcnt(3) lgkmcnt(0)
	s_barrier
	s_add_i32 s15, s28, 0x2000
	s_cmpk_lg_i32 s28, 0x4000
	s_cselect_b32 s27, s15, 0
	v_lshl_add_u32 v65, s14, 1, v239
	ds_read_b64_tr_b16 v[200:201], v65 offset:24576
	ds_read_b64_tr_b16 v[202:203], v65 offset:25088
	s_waitcnt lgkmcnt(9)
	v_mfma_f32_32x32x16_bf16 v[96:111], v[72:75], v[168:171], 0
	v_add_f32_e32 v80, v128, v129
	v_add_f32_e32 v80, v130, v80
	v_add_f32_e32 v80, v131, v80
	v_add_f32_e32 v80, v132, v80
	v_add_f32_e32 v80, v133, v80
	v_cvt_pk_bf16_f32 v172, v128, v129
	v_cvt_pk_bf16_f32 v173, v130, v131
	ds_read_b64_tr_b16 v[72:73], v65 offset:28672
	ds_read_b64_tr_b16 v[74:75], v65 offset:29184
	v_add_f32_e32 v80, v134, v80
	v_add_f32_e32 v80, v135, v80
	v_add_f32_e32 v80, v136, v80
	v_add_f32_e32 v128, v137, v80
	s_waitcnt lgkmcnt(10)
	v_mfma_f32_32x32x16_bf16 v[80:95], v[76:79], v[168:171], 0
	v_cvt_pk_bf16_f32 v174, v132, v133
	v_cvt_pk_bf16_f32 v175, v134, v135
	ds_read_b64_tr_b16 v[76:77], v65 offset:32768
	ds_read_b64_tr_b16 v[78:79], v65 offset:33280
	s_waitcnt lgkmcnt(11)
	v_mfma_f32_32x32x16_bf16 v[96:111], v[176:179], v[160:163], v[96:111]
	v_add_f32_e32 v128, v138, v128
	v_add_f32_e32 v128, v139, v128
	v_add_f32_e32 v128, v140, v128
	v_add_f32_e32 v132, v141, v128
	v_cvt_pk_bf16_f32 v164, v136, v137
	v_cvt_pk_bf16_f32 v165, v138, v139
	ds_read_b64_tr_b16 v[128:129], v65 offset:36864
	ds_read_b64_tr_b16 v[130:131], v65 offset:37376
	s_waitcnt lgkmcnt(12)
	v_mfma_f32_32x32x16_bf16 v[80:95], v[180:183], v[160:163], v[80:95]
	v_add_f32_e32 v132, v142, v132
	v_add_f32_e32 v132, v143, v132
	v_add_f32_e32 v132, v112, v132
	v_add_f32_e32 v136, v113, v132
	v_cvt_pk_bf16_f32 v166, v140, v141
	v_cvt_pk_bf16_f32 v167, v142, v143
	ds_read_b64_tr_b16 v[132:133], v65 offset:25600
	ds_read_b64_tr_b16 v[134:135], v65 offset:26112
	s_waitcnt lgkmcnt(13)
	v_mfma_f32_32x32x16_bf16 v[96:111], v[184:187], v[152:155], v[96:111]
	v_add_f32_e32 v136, v114, v136
	v_add_f32_e32 v136, v115, v136
	v_add_f32_e32 v136, v116, v136
	v_add_f32_e32 v136, v117, v136
	v_cvt_pk_bf16_f32 v156, v112, v113
	v_cvt_pk_bf16_f32 v157, v114, v115
	ds_read_b64_tr_b16 v[112:113], v65 offset:29696
	ds_read_b64_tr_b16 v[114:115], v65 offset:30208
	s_waitcnt lgkmcnt(14)
	v_mfma_f32_32x32x16_bf16 v[80:95], v[188:191], v[152:155], v[80:95]
	v_add_f32_e32 v136, v118, v136
	v_add_f32_e32 v136, v119, v136
	v_add_f32_e32 v136, v120, v136
	v_add_f32_e32 v136, v121, v136
	v_cvt_pk_bf16_f32 v158, v116, v117
	v_cvt_pk_bf16_f32 v159, v118, v119
	ds_read_b64_tr_b16 v[116:117], v65 offset:33792
	ds_read_b64_tr_b16 v[118:119], v65 offset:34304
	s_waitcnt lgkmcnt(14)
	v_mfma_f32_32x32x16_bf16 v[96:111], v[192:195], v[144:147], v[96:111]
	v_add_f32_e32 v136, v122, v136
	v_add_f32_e32 v136, v123, v136
	v_add_f32_e32 v136, v124, v136
	v_add_f32_e32 v136, v125, v136
	v_cvt_pk_bf16_f32 v148, v120, v121
	v_cvt_pk_bf16_f32 v149, v122, v123
	ds_read_b64_tr_b16 v[120:121], v65 offset:37888
	ds_read_b64_tr_b16 v[122:123], v65 offset:38400
	v_mfma_f32_32x32x16_bf16 v[80:95], v[196:199], v[144:147], v[80:95]
	v_add_f32_e32 v136, v126, v136
	v_add_f32_e32 v136, v127, v136
	v_cvt_pk_bf16_f32 v150, v124, v125
	v_cvt_pk_bf16_f32 v151, v126, v127
	v_add_f32_e32 v64, v64, v136
	s_add_i32 s35, s35, 2
	s_waitcnt lgkmcnt(14)
	v_mfma_f32_32x32x16_bf16 v[48:63], v[172:175], v[200:203], v[48:63]
	ds_read_b64_tr_b16 v[68:69], v65 offset:26624
	ds_read_b64_tr_b16 v[70:71], v65 offset:27136
	v_exp_f32_e32 v96, v96
	v_exp_f32_e32 v97, v97
	s_waitcnt lgkmcnt(14)
	v_mfma_f32_32x32x16_bf16 v[32:47], v[172:175], v[72:75], v[32:47]
	v_exp_f32_e32 v98, v98
	v_exp_f32_e32 v99, v99
	ds_read_b64_tr_b16 v[72:73], v65 offset:30720
	ds_read_b64_tr_b16 v[74:75], v65 offset:31232
	s_add_i32 m0, s28, s20
	s_nop 0
	global_load_lds_dwordx4 v250, s[98:99]
	s_add_u32 s98, s98, 0x60000
	s_addc_u32 s99, s99, 0
	s_waitcnt lgkmcnt(14)
; #define WAIT_BAR(N) asm volatile("s_waitcnt vmcnt(" #N ") lgkmcnt(0)\n\ts_barrier":::"memory")
;   #define ROT() do{sl_prev=sl_cur;sl_cur=sl_next;sl_next=(sl_next==(NSLOT-1)*SLOTB)?0:sl_next+SLOTB;}while(0)
; template<int DUMMY> __device__ __forceinline__ void attn_pass2(const bf16*Qh,const bf16*__restrict__ Kh,const bf16*__restrict__ Vh,const int q0,char*shm,f32x16 (&o)[4]){
;     ...
;   int t=1;
;     ...
;   for(;t+5<NT;t+=2){
;     STEP(pB0,pB1,pA0,pA1,t,true,true,true);     WAIT_BAR(3); ROT();
;     STEP(pA0,pA1,pB0,pB1,t+1,true,true,true);   WAIT_BAR(3); ROT();
	v_mfma_f32_32x32x16_bf16 v[16:31], v[172:175], v[76:79], v[16:31]
	v_exp_f32_e32 v100, v100
	v_exp_f32_e32 v101, v101
	ds_read_b64_tr_b16 v[76:77], v65 offset:34816
	ds_read_b64_tr_b16 v[78:79], v65 offset:35328
	s_waitcnt lgkmcnt(14)
	v_mfma_f32_32x32x16_bf16 v[0:15], v[172:175], v[128:131], v[0:15]
	v_exp_f32_e32 v102, v102
	v_exp_f32_e32 v103, v103
	ds_read_b64_tr_b16 v[124:125], v65 offset:38912
	ds_read_b64_tr_b16 v[126:127], v65 offset:39424
	s_waitcnt lgkmcnt(14)
	v_mfma_f32_32x32x16_bf16 v[48:63], v[164:167], v[132:135], v[48:63]
	v_exp_f32_e32 v104, v104
	v_exp_f32_e32 v105, v105
	ds_read_b64_tr_b16 v[128:129], v65 offset:27648
	ds_read_b64_tr_b16 v[130:131], v65 offset:28160
	s_lshl_b32 s24, s27, 1
	s_add_i32 s24, s24, s21
	s_mov_b32 m0, s24
	s_nop 0
	global_load_lds_dwordx4 v251, s[100:101]
	s_waitcnt lgkmcnt(14)
	v_mfma_f32_32x32x16_bf16 v[32:47], v[164:167], v[112:115], v[32:47]
	v_exp_f32_e32 v106, v106
	v_exp_f32_e32 v107, v107
	ds_read_b64_tr_b16 v[112:113], v65 offset:31744
	ds_read_b64_tr_b16 v[114:115], v65 offset:32256
	s_waitcnt lgkmcnt(14)
	v_mfma_f32_32x32x16_bf16 v[16:31], v[164:167], v[116:119], v[16:31]
	v_exp_f32_e32 v108, v108
	v_exp_f32_e32 v109, v109
	ds_read_b64_tr_b16 v[116:117], v65 offset:35840
	ds_read_b64_tr_b16 v[118:119], v65 offset:36352
	s_waitcnt lgkmcnt(14)
	v_mfma_f32_32x32x16_bf16 v[0:15], v[164:167], v[120:123], v[0:15]
	v_exp_f32_e32 v110, v110
	v_exp_f32_e32 v111, v111
	ds_read_b64_tr_b16 v[120:121], v65 offset:39936
	ds_read_b64_tr_b16 v[122:123], v65 offset:40448
	s_add_i32 m0, s24, 0x1f80
	s_nop 0
	global_load_lds_dwordx4 v251, s[100:101] offset:128
	s_add_u32 s100, s100, 0x60000
	s_addc_u32 s101, s101, 0
	s_waitcnt lgkmcnt(14)
	v_mfma_f32_32x32x16_bf16 v[48:63], v[156:159], v[68:71], v[48:63]
	v_exp_f32_e32 v80, v80
	v_exp_f32_e32 v81, v81
	s_waitcnt lgkmcnt(12)
	v_mfma_f32_32x32x16_bf16 v[32:47], v[156:159], v[72:75], v[32:47]
	v_exp_f32_e32 v82, v82
	v_exp_f32_e32 v83, v83
	v_add_u32_e32 v65, s27, v241
	ds_read_b128 v[204:207], v65
	ds_read_b128 v[200:203], v65 offset:512
	s_waitcnt lgkmcnt(12)
	v_mfma_f32_32x32x16_bf16 v[16:31], v[156:159], v[76:79], v[16:31]
	v_exp_f32_e32 v84, v84
	v_exp_f32_e32 v85, v85
	ds_read_b128 v[196:199], v65 offset:2048
	ds_read_b128 v[192:195], v65 offset:2560
	s_waitcnt lgkmcnt(12)
	v_mfma_f32_32x32x16_bf16 v[0:15], v[156:159], v[124:127], v[0:15]
	v_exp_f32_e32 v86, v86
	v_exp_f32_e32 v87, v87
	ds_read_b128 v[188:191], v65 offset:4096
	ds_read_b128 v[184:187], v65 offset:4608
	s_waitcnt lgkmcnt(12)
	v_mfma_f32_32x32x16_bf16 v[48:63], v[148:151], v[128:131], v[48:63]
	v_exp_f32_e32 v88, v88
	v_exp_f32_e32 v89, v89
	ds_read_b128 v[180:183], v65 offset:6144
	ds_read_b128 v[176:179], v65 offset:6656
	s_waitcnt lgkmcnt(12)
	v_mfma_f32_32x32x16_bf16 v[32:47], v[148:151], v[112:115], v[32:47]
	v_exp_f32_e32 v90, v90
	v_exp_f32_e32 v91, v91
	s_waitcnt lgkmcnt(10)
	v_mfma_f32_32x32x16_bf16 v[16:31], v[148:151], v[116:119], v[16:31]
	v_exp_f32_e32 v92, v92
	v_exp_f32_e32 v93, v93
	s_waitcnt lgkmcnt(8)
	v_mfma_f32_32x32x16_bf16 v[0:15], v[148:151], v[120:123], v[0:15]
	v_exp_f32_e32 v94, v94
	v_exp_f32_e32 v95, v95
	s_add_i32 s14, s27, 0x2000
	s_cmpk_lg_i32 s27, 0x4000
	s_waitcnt vmcnt(3) lgkmcnt(0)
	s_barrier
	s_cselect_b32 s28, s14, 0
	s_add_u32 s56, s56, 0xc0000
	s_addc_u32 s57, s57, 0
	s_cmp_ge_i32 s35, s11
	s_mov_b32 s15, s37
	s_cbranch_scc0 .LBB0_304
	s_setprio 0
	s_ashr_i32 s11, s10, 31
	s_add_i32 s14, s35, 1
	s_cmp_lt_i32 s14, s25
	s_cbranch_scc1 .LBB0_315
